# init phase adaLN projection loop: weight-row loads batched 16 per chunk and double buffered instead of one load then vmcnt(0) per k (bit-identical FMA order)
# speedup vs baseline: 1.0102x; 1.0102x over previous
; DI void phase_init(const Ctx& c) {
;     ...
;       const int col = tid & 63, kq = tid >> 6;
;       float acc[9];
; #pragma unroll
;       for (int b = 0; b < 9; ++b) acc[b] = 0.f;
;       const float* w = P.in[4] + (size_t)l * 1024 * 6144 + n0 + col;
;       for (int k = kq * 128; k < kq * 128 + 128; ++k) {
;         const float wv = w[(size_t)k * 6144];
; #pragma unroll
;         for (int b = 0; b < 9; ++b) acc[b] += sc[b * 1024 + k] * wv;
.LBB0_54:
	v_lshl_add_u64 v[58:59], v[56:57], 0, s[16:17]
	global_load_dword v80, v[58:59], off
	v_add_co_u32_e32 v58, vcc, 0x6000, v58
	s_nop 1
	v_addc_co_u32_e32 v59, vcc, 0, v59, vcc
	global_load_dword v81, v[58:59], off
	v_add_co_u32_e32 v58, vcc, 0x6000, v58
	s_nop 1
	v_addc_co_u32_e32 v59, vcc, 0, v59, vcc
	global_load_dword v82, v[58:59], off
	v_add_co_u32_e32 v58, vcc, 0x6000, v58
	s_nop 1
	v_addc_co_u32_e32 v59, vcc, 0, v59, vcc
	global_load_dword v83, v[58:59], off
	v_add_co_u32_e32 v58, vcc, 0x6000, v58
	s_nop 1
	v_addc_co_u32_e32 v59, vcc, 0, v59, vcc
	global_load_dword v84, v[58:59], off
	v_add_co_u32_e32 v58, vcc, 0x6000, v58
	s_nop 1
	v_addc_co_u32_e32 v59, vcc, 0, v59, vcc
	global_load_dword v85, v[58:59], off
	v_add_co_u32_e32 v58, vcc, 0x6000, v58
	s_nop 1
	v_addc_co_u32_e32 v59, vcc, 0, v59, vcc
	global_load_dword v86, v[58:59], off
	v_add_co_u32_e32 v58, vcc, 0x6000, v58
	s_nop 1
	v_addc_co_u32_e32 v59, vcc, 0, v59, vcc
	global_load_dword v87, v[58:59], off
	v_add_co_u32_e32 v58, vcc, 0x6000, v58
	s_nop 1
	v_addc_co_u32_e32 v59, vcc, 0, v59, vcc
	global_load_dword v88, v[58:59], off
	v_add_co_u32_e32 v58, vcc, 0x6000, v58
	s_nop 1
	v_addc_co_u32_e32 v59, vcc, 0, v59, vcc
	global_load_dword v89, v[58:59], off
	v_add_co_u32_e32 v58, vcc, 0x6000, v58
	s_nop 1
	v_addc_co_u32_e32 v59, vcc, 0, v59, vcc
	global_load_dword v90, v[58:59], off
	v_add_co_u32_e32 v58, vcc, 0x6000, v58
	s_nop 1
	v_addc_co_u32_e32 v59, vcc, 0, v59, vcc
	global_load_dword v91, v[58:59], off
	v_add_co_u32_e32 v58, vcc, 0x6000, v58
	s_nop 1
	v_addc_co_u32_e32 v59, vcc, 0, v59, vcc
	global_load_dword v92, v[58:59], off
	v_add_co_u32_e32 v58, vcc, 0x6000, v58
	s_nop 1
	v_addc_co_u32_e32 v59, vcc, 0, v59, vcc
	global_load_dword v93, v[58:59], off
	v_add_co_u32_e32 v58, vcc, 0x6000, v58
	s_nop 1
	v_addc_co_u32_e32 v59, vcc, 0, v59, vcc
	global_load_dword v94, v[58:59], off
	v_add_co_u32_e32 v58, vcc, 0x6000, v58
	s_nop 1
	v_addc_co_u32_e32 v59, vcc, 0, v59, vcc
	global_load_dword v95, v[58:59], off
	v_add_co_u32_e32 v58, vcc, 0x6000, v58
	s_nop 1
	v_addc_co_u32_e32 v59, vcc, 0, v59, vcc
	s_mov_b32 s24, 0
.Lmod_trip:
	global_load_dword v96, v[58:59], off
	v_add_co_u32_e32 v58, vcc, 0x6000, v58
	s_nop 1
	v_addc_co_u32_e32 v59, vcc, 0, v59, vcc
	global_load_dword v97, v[58:59], off
	v_add_co_u32_e32 v58, vcc, 0x6000, v58
	s_nop 1
	v_addc_co_u32_e32 v59, vcc, 0, v59, vcc
	global_load_dword v98, v[58:59], off
	v_add_co_u32_e32 v58, vcc, 0x6000, v58
	s_nop 1
	v_addc_co_u32_e32 v59, vcc, 0, v59, vcc
	global_load_dword v99, v[58:59], off
	v_add_co_u32_e32 v58, vcc, 0x6000, v58
	s_nop 1
	v_addc_co_u32_e32 v59, vcc, 0, v59, vcc
	global_load_dword v100, v[58:59], off
	v_add_co_u32_e32 v58, vcc, 0x6000, v58
	s_nop 1
	v_addc_co_u32_e32 v59, vcc, 0, v59, vcc
	global_load_dword v101, v[58:59], off
	v_add_co_u32_e32 v58, vcc, 0x6000, v58
	s_nop 1
	v_addc_co_u32_e32 v59, vcc, 0, v59, vcc
	global_load_dword v102, v[58:59], off
	v_add_co_u32_e32 v58, vcc, 0x6000, v58
	s_nop 1
	v_addc_co_u32_e32 v59, vcc, 0, v59, vcc
	global_load_dword v103, v[58:59], off
	v_add_co_u32_e32 v58, vcc, 0x6000, v58
	s_nop 1
	v_addc_co_u32_e32 v59, vcc, 0, v59, vcc
	global_load_dword v104, v[58:59], off
	v_add_co_u32_e32 v58, vcc, 0x6000, v58
	s_nop 1
	v_addc_co_u32_e32 v59, vcc, 0, v59, vcc
	global_load_dword v105, v[58:59], off
	v_add_co_u32_e32 v58, vcc, 0x6000, v58
	s_nop 1
	v_addc_co_u32_e32 v59, vcc, 0, v59, vcc
	global_load_dword v106, v[58:59], off
	v_add_co_u32_e32 v58, vcc, 0x6000, v58
	s_nop 1
	v_addc_co_u32_e32 v59, vcc, 0, v59, vcc
	global_load_dword v107, v[58:59], off
	v_add_co_u32_e32 v58, vcc, 0x6000, v58
	s_nop 1
	v_addc_co_u32_e32 v59, vcc, 0, v59, vcc
	global_load_dword v108, v[58:59], off
	v_add_co_u32_e32 v58, vcc, 0x6000, v58
	s_nop 1
	v_addc_co_u32_e32 v59, vcc, 0, v59, vcc
	global_load_dword v109, v[58:59], off
	v_add_co_u32_e32 v58, vcc, 0x6000, v58
	s_nop 1
	v_addc_co_u32_e32 v59, vcc, 0, v59, vcc
	global_load_dword v110, v[58:59], off
	v_add_co_u32_e32 v58, vcc, 0x6000, v58
	s_nop 1
	v_addc_co_u32_e32 v59, vcc, 0, v59, vcc
	global_load_dword v111, v[58:59], off
	v_add_co_u32_e32 v58, vcc, 0x6000, v58
	s_nop 1
	v_addc_co_u32_e32 v59, vcc, 0, v59, vcc
	ds_read_b128 v[112:115], v66
	ds_read_b128 v[116:119], v66 offset:4096
	ds_read_b128 v[120:123], v66 offset:8192
	ds_read_b128 v[124:127], v66 offset:12288
	ds_read_b128 v[128:131], v66 offset:16384
	ds_read_b128 v[132:135], v66 offset:20480
	ds_read_b128 v[136:139], v66 offset:24576
	ds_read_b128 v[140:143], v66 offset:28672
	ds_read_b128 v[144:147], v66 offset:32768
	s_waitcnt lgkmcnt(0)
	s_waitcnt vmcnt(31)
	v_fmac_f32_e32 v8, v80, v112
	v_fmac_f32_e32 v9, v80, v116
	v_fmac_f32_e32 v16, v80, v120
	v_fmac_f32_e32 v17, v80, v124
	v_fmac_f32_e32 v24, v80, v128
	v_fmac_f32_e32 v25, v80, v132
	v_fmac_f32_e32 v32, v80, v136
	v_fmac_f32_e32 v33, v80, v140
	v_fmac_f32_e32 v67, v80, v144
	s_waitcnt vmcnt(30)
	v_fmac_f32_e32 v8, v81, v113
	v_fmac_f32_e32 v9, v81, v117
	v_fmac_f32_e32 v16, v81, v121
	v_fmac_f32_e32 v17, v81, v125
	v_fmac_f32_e32 v24, v81, v129
	v_fmac_f32_e32 v25, v81, v133
	v_fmac_f32_e32 v32, v81, v137
	v_fmac_f32_e32 v33, v81, v141
	v_fmac_f32_e32 v67, v81, v145
	s_waitcnt vmcnt(29)
	v_fmac_f32_e32 v8, v82, v114
	v_fmac_f32_e32 v9, v82, v118
	v_fmac_f32_e32 v16, v82, v122
	v_fmac_f32_e32 v17, v82, v126
	v_fmac_f32_e32 v24, v82, v130
	v_fmac_f32_e32 v25, v82, v134
	v_fmac_f32_e32 v32, v82, v138
	v_fmac_f32_e32 v33, v82, v142
	v_fmac_f32_e32 v67, v82, v146
	s_waitcnt vmcnt(28)
; DI void phase_init(const Ctx& c) {
;     ...
;       for (int k = kq * 128; k < kq * 128 + 128; ++k) {
;         const float wv = w[(size_t)k * 6144];
; #pragma unroll
;         for (int b = 0; b < 9; ++b) acc[b] += sc[b * 1024 + k] * wv;
	v_fmac_f32_e32 v8, v83, v115
	v_fmac_f32_e32 v9, v83, v119
	v_fmac_f32_e32 v16, v83, v123
	v_fmac_f32_e32 v17, v83, v127
	v_fmac_f32_e32 v24, v83, v131
	v_fmac_f32_e32 v25, v83, v135
	v_fmac_f32_e32 v32, v83, v139
	v_fmac_f32_e32 v33, v83, v143
	v_fmac_f32_e32 v67, v83, v147
	ds_read_b128 v[112:115], v66 offset:16
	ds_read_b128 v[116:119], v66 offset:4112
	ds_read_b128 v[120:123], v66 offset:8208
	ds_read_b128 v[124:127], v66 offset:12304
	ds_read_b128 v[128:131], v66 offset:16400
	ds_read_b128 v[132:135], v66 offset:20496
	ds_read_b128 v[136:139], v66 offset:24592
	ds_read_b128 v[140:143], v66 offset:28688
	ds_read_b128 v[144:147], v66 offset:32784
	s_waitcnt lgkmcnt(0)
	s_waitcnt vmcnt(27)
	v_fmac_f32_e32 v8, v84, v112
	v_fmac_f32_e32 v9, v84, v116
	v_fmac_f32_e32 v16, v84, v120
	v_fmac_f32_e32 v17, v84, v124
	v_fmac_f32_e32 v24, v84, v128
	v_fmac_f32_e32 v25, v84, v132
	v_fmac_f32_e32 v32, v84, v136
	v_fmac_f32_e32 v33, v84, v140
	v_fmac_f32_e32 v67, v84, v144
	s_waitcnt vmcnt(26)
	v_fmac_f32_e32 v8, v85, v113
	v_fmac_f32_e32 v9, v85, v117
	v_fmac_f32_e32 v16, v85, v121
	v_fmac_f32_e32 v17, v85, v125
	v_fmac_f32_e32 v24, v85, v129
	v_fmac_f32_e32 v25, v85, v133
	v_fmac_f32_e32 v32, v85, v137
	v_fmac_f32_e32 v33, v85, v141
	v_fmac_f32_e32 v67, v85, v145
	s_waitcnt vmcnt(25)
	v_fmac_f32_e32 v8, v86, v114
	v_fmac_f32_e32 v9, v86, v118
	v_fmac_f32_e32 v16, v86, v122
	v_fmac_f32_e32 v17, v86, v126
	v_fmac_f32_e32 v24, v86, v130
	v_fmac_f32_e32 v25, v86, v134
	v_fmac_f32_e32 v32, v86, v138
	v_fmac_f32_e32 v33, v86, v142
	v_fmac_f32_e32 v67, v86, v146
	s_waitcnt vmcnt(24)
	v_fmac_f32_e32 v8, v87, v115
	v_fmac_f32_e32 v9, v87, v119
	v_fmac_f32_e32 v16, v87, v123
	v_fmac_f32_e32 v17, v87, v127
	v_fmac_f32_e32 v24, v87, v131
	v_fmac_f32_e32 v25, v87, v135
	v_fmac_f32_e32 v32, v87, v139
	v_fmac_f32_e32 v33, v87, v143
	v_fmac_f32_e32 v67, v87, v147
	ds_read_b128 v[112:115], v66 offset:32
	ds_read_b128 v[116:119], v66 offset:4128
	ds_read_b128 v[120:123], v66 offset:8224
	ds_read_b128 v[124:127], v66 offset:12320
	ds_read_b128 v[128:131], v66 offset:16416
	ds_read_b128 v[132:135], v66 offset:20512
	ds_read_b128 v[136:139], v66 offset:24608
	ds_read_b128 v[140:143], v66 offset:28704
	ds_read_b128 v[144:147], v66 offset:32800
	s_waitcnt lgkmcnt(0)
	s_waitcnt vmcnt(23)
	v_fmac_f32_e32 v8, v88, v112
	v_fmac_f32_e32 v9, v88, v116
	v_fmac_f32_e32 v16, v88, v120
	v_fmac_f32_e32 v17, v88, v124
	v_fmac_f32_e32 v24, v88, v128
	v_fmac_f32_e32 v25, v88, v132
	v_fmac_f32_e32 v32, v88, v136
	v_fmac_f32_e32 v33, v88, v140
	v_fmac_f32_e32 v67, v88, v144
	s_waitcnt vmcnt(22)
	v_fmac_f32_e32 v8, v89, v113
	v_fmac_f32_e32 v9, v89, v117
	v_fmac_f32_e32 v16, v89, v121
	v_fmac_f32_e32 v17, v89, v125
	v_fmac_f32_e32 v24, v89, v129
	v_fmac_f32_e32 v25, v89, v133
	v_fmac_f32_e32 v32, v89, v137
	v_fmac_f32_e32 v33, v89, v141
	v_fmac_f32_e32 v67, v89, v145
	s_waitcnt vmcnt(21)
	v_fmac_f32_e32 v8, v90, v114
	v_fmac_f32_e32 v9, v90, v118
	v_fmac_f32_e32 v16, v90, v122
	v_fmac_f32_e32 v17, v90, v126
	v_fmac_f32_e32 v24, v90, v130
	v_fmac_f32_e32 v25, v90, v134
	v_fmac_f32_e32 v32, v90, v138
	v_fmac_f32_e32 v33, v90, v142
	v_fmac_f32_e32 v67, v90, v146
	s_waitcnt vmcnt(20)
	v_fmac_f32_e32 v8, v91, v115
	v_fmac_f32_e32 v9, v91, v119
	v_fmac_f32_e32 v16, v91, v123
	v_fmac_f32_e32 v17, v91, v127
	v_fmac_f32_e32 v24, v91, v131
	v_fmac_f32_e32 v25, v91, v135
	v_fmac_f32_e32 v32, v91, v139
	v_fmac_f32_e32 v33, v91, v143
	v_fmac_f32_e32 v67, v91, v147
	ds_read_b128 v[112:115], v66 offset:48
	ds_read_b128 v[116:119], v66 offset:4144
	ds_read_b128 v[120:123], v66 offset:8240
	ds_read_b128 v[124:127], v66 offset:12336
	ds_read_b128 v[128:131], v66 offset:16432
	ds_read_b128 v[132:135], v66 offset:20528
	ds_read_b128 v[136:139], v66 offset:24624
	ds_read_b128 v[140:143], v66 offset:28720
	ds_read_b128 v[144:147], v66 offset:32816
	s_waitcnt lgkmcnt(0)
	s_waitcnt vmcnt(19)
	v_fmac_f32_e32 v8, v92, v112
	v_fmac_f32_e32 v9, v92, v116
	v_fmac_f32_e32 v16, v92, v120
	v_fmac_f32_e32 v17, v92, v124
	v_fmac_f32_e32 v24, v92, v128
	v_fmac_f32_e32 v25, v92, v132
	v_fmac_f32_e32 v32, v92, v136
	v_fmac_f32_e32 v33, v92, v140
	v_fmac_f32_e32 v67, v92, v144
	s_waitcnt vmcnt(18)
	v_fmac_f32_e32 v8, v93, v113
	v_fmac_f32_e32 v9, v93, v117
	v_fmac_f32_e32 v16, v93, v121
	v_fmac_f32_e32 v17, v93, v125
	v_fmac_f32_e32 v24, v93, v129
	v_fmac_f32_e32 v25, v93, v133
	v_fmac_f32_e32 v32, v93, v137
	v_fmac_f32_e32 v33, v93, v141
	v_fmac_f32_e32 v67, v93, v145
	s_waitcnt vmcnt(17)
	v_fmac_f32_e32 v8, v94, v114
	v_fmac_f32_e32 v9, v94, v118
	v_fmac_f32_e32 v16, v94, v122
	v_fmac_f32_e32 v17, v94, v126
	v_fmac_f32_e32 v24, v94, v130
	v_fmac_f32_e32 v25, v94, v134
	v_fmac_f32_e32 v32, v94, v138
	v_fmac_f32_e32 v33, v94, v142
	v_fmac_f32_e32 v67, v94, v146
	s_waitcnt vmcnt(16)
	v_fmac_f32_e32 v8, v95, v115
	v_fmac_f32_e32 v9, v95, v119
	v_fmac_f32_e32 v16, v95, v123
	v_fmac_f32_e32 v17, v95, v127
	v_fmac_f32_e32 v24, v95, v131
	v_fmac_f32_e32 v25, v95, v135
	v_fmac_f32_e32 v32, v95, v139
	v_fmac_f32_e32 v33, v95, v143
	v_fmac_f32_e32 v67, v95, v147
	v_add_u32_e32 v66, 64, v66
	s_cmp_eq_u32 s24, 3
	s_cbranch_scc1 .Lmod_last
; DI void phase_init(const Ctx& c) {
;     ...
;       for (int k = kq * 128; k < kq * 128 + 128; ++k) {
;         const float wv = w[(size_t)k * 6144];
; #pragma unroll
;         for (int b = 0; b < 9; ++b) acc[b] += sc[b * 1024 + k] * wv;
	global_load_dword v80, v[58:59], off
	v_add_co_u32_e32 v58, vcc, 0x6000, v58
	s_nop 1
	v_addc_co_u32_e32 v59, vcc, 0, v59, vcc
	global_load_dword v81, v[58:59], off
	v_add_co_u32_e32 v58, vcc, 0x6000, v58
	s_nop 1
	v_addc_co_u32_e32 v59, vcc, 0, v59, vcc
	global_load_dword v82, v[58:59], off
	v_add_co_u32_e32 v58, vcc, 0x6000, v58
	s_nop 1
	v_addc_co_u32_e32 v59, vcc, 0, v59, vcc
	global_load_dword v83, v[58:59], off
	v_add_co_u32_e32 v58, vcc, 0x6000, v58
	s_nop 1
	v_addc_co_u32_e32 v59, vcc, 0, v59, vcc
	global_load_dword v84, v[58:59], off
	v_add_co_u32_e32 v58, vcc, 0x6000, v58
	s_nop 1
	v_addc_co_u32_e32 v59, vcc, 0, v59, vcc
	global_load_dword v85, v[58:59], off
	v_add_co_u32_e32 v58, vcc, 0x6000, v58
	s_nop 1
	v_addc_co_u32_e32 v59, vcc, 0, v59, vcc
	global_load_dword v86, v[58:59], off
	v_add_co_u32_e32 v58, vcc, 0x6000, v58
	s_nop 1
	v_addc_co_u32_e32 v59, vcc, 0, v59, vcc
	global_load_dword v87, v[58:59], off
	v_add_co_u32_e32 v58, vcc, 0x6000, v58
	s_nop 1
	v_addc_co_u32_e32 v59, vcc, 0, v59, vcc
	global_load_dword v88, v[58:59], off
	v_add_co_u32_e32 v58, vcc, 0x6000, v58
	s_nop 1
	v_addc_co_u32_e32 v59, vcc, 0, v59, vcc
	global_load_dword v89, v[58:59], off
	v_add_co_u32_e32 v58, vcc, 0x6000, v58
	s_nop 1
	v_addc_co_u32_e32 v59, vcc, 0, v59, vcc
	global_load_dword v90, v[58:59], off
	v_add_co_u32_e32 v58, vcc, 0x6000, v58
	s_nop 1
	v_addc_co_u32_e32 v59, vcc, 0, v59, vcc
	global_load_dword v91, v[58:59], off
	v_add_co_u32_e32 v58, vcc, 0x6000, v58
	s_nop 1
	v_addc_co_u32_e32 v59, vcc, 0, v59, vcc
	global_load_dword v92, v[58:59], off
	v_add_co_u32_e32 v58, vcc, 0x6000, v58
	s_nop 1
	v_addc_co_u32_e32 v59, vcc, 0, v59, vcc
	global_load_dword v93, v[58:59], off
	v_add_co_u32_e32 v58, vcc, 0x6000, v58
	s_nop 1
	v_addc_co_u32_e32 v59, vcc, 0, v59, vcc
	global_load_dword v94, v[58:59], off
	v_add_co_u32_e32 v58, vcc, 0x6000, v58
	s_nop 1
	v_addc_co_u32_e32 v59, vcc, 0, v59, vcc
	global_load_dword v95, v[58:59], off
	v_add_co_u32_e32 v58, vcc, 0x6000, v58
	s_nop 1
	v_addc_co_u32_e32 v59, vcc, 0, v59, vcc
	ds_read_b128 v[112:115], v66
	ds_read_b128 v[116:119], v66 offset:4096
	ds_read_b128 v[120:123], v66 offset:8192
	ds_read_b128 v[124:127], v66 offset:12288
	ds_read_b128 v[128:131], v66 offset:16384
	ds_read_b128 v[132:135], v66 offset:20480
	ds_read_b128 v[136:139], v66 offset:24576
	ds_read_b128 v[140:143], v66 offset:28672
	ds_read_b128 v[144:147], v66 offset:32768
	s_waitcnt lgkmcnt(0)
	s_waitcnt vmcnt(31)
	v_fmac_f32_e32 v8, v96, v112
	v_fmac_f32_e32 v9, v96, v116
	v_fmac_f32_e32 v16, v96, v120
	v_fmac_f32_e32 v17, v96, v124
	v_fmac_f32_e32 v24, v96, v128
	v_fmac_f32_e32 v25, v96, v132
	v_fmac_f32_e32 v32, v96, v136
	v_fmac_f32_e32 v33, v96, v140
	v_fmac_f32_e32 v67, v96, v144
	s_waitcnt vmcnt(30)
	v_fmac_f32_e32 v8, v97, v113
	v_fmac_f32_e32 v9, v97, v117
	v_fmac_f32_e32 v16, v97, v121
	v_fmac_f32_e32 v17, v97, v125
	v_fmac_f32_e32 v24, v97, v129
	v_fmac_f32_e32 v25, v97, v133
	v_fmac_f32_e32 v32, v97, v137
	v_fmac_f32_e32 v33, v97, v141
	v_fmac_f32_e32 v67, v97, v145
	s_waitcnt vmcnt(29)
	v_fmac_f32_e32 v8, v98, v114
	v_fmac_f32_e32 v9, v98, v118
	v_fmac_f32_e32 v16, v98, v122
	v_fmac_f32_e32 v17, v98, v126
	v_fmac_f32_e32 v24, v98, v130
	v_fmac_f32_e32 v25, v98, v134
	v_fmac_f32_e32 v32, v98, v138
	v_fmac_f32_e32 v33, v98, v142
	v_fmac_f32_e32 v67, v98, v146
	s_waitcnt vmcnt(28)
	v_fmac_f32_e32 v8, v99, v115
	v_fmac_f32_e32 v9, v99, v119
	v_fmac_f32_e32 v16, v99, v123
	v_fmac_f32_e32 v17, v99, v127
	v_fmac_f32_e32 v24, v99, v131
	v_fmac_f32_e32 v25, v99, v135
	v_fmac_f32_e32 v32, v99, v139
	v_fmac_f32_e32 v33, v99, v143
	v_fmac_f32_e32 v67, v99, v147
	ds_read_b128 v[112:115], v66 offset:16
	ds_read_b128 v[116:119], v66 offset:4112
	ds_read_b128 v[120:123], v66 offset:8208
	ds_read_b128 v[124:127], v66 offset:12304
	ds_read_b128 v[128:131], v66 offset:16400
	ds_read_b128 v[132:135], v66 offset:20496
	ds_read_b128 v[136:139], v66 offset:24592
	ds_read_b128 v[140:143], v66 offset:28688
	ds_read_b128 v[144:147], v66 offset:32784
	s_waitcnt lgkmcnt(0)
	s_waitcnt vmcnt(27)
	v_fmac_f32_e32 v8, v100, v112
	v_fmac_f32_e32 v9, v100, v116
	v_fmac_f32_e32 v16, v100, v120
	v_fmac_f32_e32 v17, v100, v124
	v_fmac_f32_e32 v24, v100, v128
	v_fmac_f32_e32 v25, v100, v132
	v_fmac_f32_e32 v32, v100, v136
	v_fmac_f32_e32 v33, v100, v140
	v_fmac_f32_e32 v67, v100, v144
	s_waitcnt vmcnt(26)
	v_fmac_f32_e32 v8, v101, v113
	v_fmac_f32_e32 v9, v101, v117
	v_fmac_f32_e32 v16, v101, v121
	v_fmac_f32_e32 v17, v101, v125
	v_fmac_f32_e32 v24, v101, v129
	v_fmac_f32_e32 v25, v101, v133
	v_fmac_f32_e32 v32, v101, v137
	v_fmac_f32_e32 v33, v101, v141
	v_fmac_f32_e32 v67, v101, v145
	s_waitcnt vmcnt(25)
	v_fmac_f32_e32 v8, v102, v114
	v_fmac_f32_e32 v9, v102, v118
	v_fmac_f32_e32 v16, v102, v122
	v_fmac_f32_e32 v17, v102, v126
	v_fmac_f32_e32 v24, v102, v130
	v_fmac_f32_e32 v25, v102, v134
	v_fmac_f32_e32 v32, v102, v138
	v_fmac_f32_e32 v33, v102, v142
	v_fmac_f32_e32 v67, v102, v146
	s_waitcnt vmcnt(24)
	v_fmac_f32_e32 v8, v103, v115
	v_fmac_f32_e32 v9, v103, v119
	v_fmac_f32_e32 v16, v103, v123
	v_fmac_f32_e32 v17, v103, v127
	v_fmac_f32_e32 v24, v103, v131
	v_fmac_f32_e32 v25, v103, v135
	v_fmac_f32_e32 v32, v103, v139
	v_fmac_f32_e32 v33, v103, v143
	v_fmac_f32_e32 v67, v103, v147
	ds_read_b128 v[112:115], v66 offset:32
	ds_read_b128 v[116:119], v66 offset:4128
	ds_read_b128 v[120:123], v66 offset:8224
	ds_read_b128 v[124:127], v66 offset:12320
	ds_read_b128 v[128:131], v66 offset:16416
	ds_read_b128 v[132:135], v66 offset:20512
	ds_read_b128 v[136:139], v66 offset:24608
	ds_read_b128 v[140:143], v66 offset:28704
	ds_read_b128 v[144:147], v66 offset:32800
	s_waitcnt lgkmcnt(0)
; DI void phase_init(const Ctx& c) {
;     ...
;       for (int k = kq * 128; k < kq * 128 + 128; ++k) {
;         const float wv = w[(size_t)k * 6144];
; #pragma unroll
;         for (int b = 0; b < 9; ++b) acc[b] += sc[b * 1024 + k] * wv;
	s_waitcnt vmcnt(23)
	v_fmac_f32_e32 v8, v104, v112
	v_fmac_f32_e32 v9, v104, v116
	v_fmac_f32_e32 v16, v104, v120
	v_fmac_f32_e32 v17, v104, v124
	v_fmac_f32_e32 v24, v104, v128
	v_fmac_f32_e32 v25, v104, v132
	v_fmac_f32_e32 v32, v104, v136
	v_fmac_f32_e32 v33, v104, v140
	v_fmac_f32_e32 v67, v104, v144
	s_waitcnt vmcnt(22)
	v_fmac_f32_e32 v8, v105, v113
	v_fmac_f32_e32 v9, v105, v117
	v_fmac_f32_e32 v16, v105, v121
	v_fmac_f32_e32 v17, v105, v125
	v_fmac_f32_e32 v24, v105, v129
	v_fmac_f32_e32 v25, v105, v133
	v_fmac_f32_e32 v32, v105, v137
	v_fmac_f32_e32 v33, v105, v141
	v_fmac_f32_e32 v67, v105, v145
	s_waitcnt vmcnt(21)
	v_fmac_f32_e32 v8, v106, v114
	v_fmac_f32_e32 v9, v106, v118
	v_fmac_f32_e32 v16, v106, v122
	v_fmac_f32_e32 v17, v106, v126
	v_fmac_f32_e32 v24, v106, v130
	v_fmac_f32_e32 v25, v106, v134
	v_fmac_f32_e32 v32, v106, v138
	v_fmac_f32_e32 v33, v106, v142
	v_fmac_f32_e32 v67, v106, v146
	s_waitcnt vmcnt(20)
	v_fmac_f32_e32 v8, v107, v115
	v_fmac_f32_e32 v9, v107, v119
	v_fmac_f32_e32 v16, v107, v123
	v_fmac_f32_e32 v17, v107, v127
	v_fmac_f32_e32 v24, v107, v131
	v_fmac_f32_e32 v25, v107, v135
	v_fmac_f32_e32 v32, v107, v139
	v_fmac_f32_e32 v33, v107, v143
	v_fmac_f32_e32 v67, v107, v147
	ds_read_b128 v[112:115], v66 offset:48
	ds_read_b128 v[116:119], v66 offset:4144
	ds_read_b128 v[120:123], v66 offset:8240
	ds_read_b128 v[124:127], v66 offset:12336
	ds_read_b128 v[128:131], v66 offset:16432
	ds_read_b128 v[132:135], v66 offset:20528
	ds_read_b128 v[136:139], v66 offset:24624
	ds_read_b128 v[140:143], v66 offset:28720
	ds_read_b128 v[144:147], v66 offset:32816
	s_waitcnt lgkmcnt(0)
	s_waitcnt vmcnt(19)
	v_fmac_f32_e32 v8, v108, v112
	v_fmac_f32_e32 v9, v108, v116
	v_fmac_f32_e32 v16, v108, v120
	v_fmac_f32_e32 v17, v108, v124
	v_fmac_f32_e32 v24, v108, v128
	v_fmac_f32_e32 v25, v108, v132
	v_fmac_f32_e32 v32, v108, v136
	v_fmac_f32_e32 v33, v108, v140
	v_fmac_f32_e32 v67, v108, v144
	s_waitcnt vmcnt(18)
	v_fmac_f32_e32 v8, v109, v113
	v_fmac_f32_e32 v9, v109, v117
	v_fmac_f32_e32 v16, v109, v121
	v_fmac_f32_e32 v17, v109, v125
	v_fmac_f32_e32 v24, v109, v129
	v_fmac_f32_e32 v25, v109, v133
	v_fmac_f32_e32 v32, v109, v137
	v_fmac_f32_e32 v33, v109, v141
	v_fmac_f32_e32 v67, v109, v145
	s_waitcnt vmcnt(17)
	v_fmac_f32_e32 v8, v110, v114
	v_fmac_f32_e32 v9, v110, v118
	v_fmac_f32_e32 v16, v110, v122
	v_fmac_f32_e32 v17, v110, v126
	v_fmac_f32_e32 v24, v110, v130
	v_fmac_f32_e32 v25, v110, v134
	v_fmac_f32_e32 v32, v110, v138
	v_fmac_f32_e32 v33, v110, v142
	v_fmac_f32_e32 v67, v110, v146
	s_waitcnt vmcnt(16)
	v_fmac_f32_e32 v8, v111, v115
	v_fmac_f32_e32 v9, v111, v119
	v_fmac_f32_e32 v16, v111, v123
	v_fmac_f32_e32 v17, v111, v127
	v_fmac_f32_e32 v24, v111, v131
	v_fmac_f32_e32 v25, v111, v135
	v_fmac_f32_e32 v32, v111, v139
	v_fmac_f32_e32 v33, v111, v143
	v_fmac_f32_e32 v67, v111, v147
	v_add_u32_e32 v66, 64, v66
	s_add_i32 s24, s24, 1
	s_branch .Lmod_trip
.Lmod_last:
	ds_read_b128 v[112:115], v66
	ds_read_b128 v[116:119], v66 offset:4096
	ds_read_b128 v[120:123], v66 offset:8192
	ds_read_b128 v[124:127], v66 offset:12288
	ds_read_b128 v[128:131], v66 offset:16384
	ds_read_b128 v[132:135], v66 offset:20480
	ds_read_b128 v[136:139], v66 offset:24576
	ds_read_b128 v[140:143], v66 offset:28672
	ds_read_b128 v[144:147], v66 offset:32768
	s_waitcnt lgkmcnt(0)
	s_waitcnt vmcnt(15)
	v_fmac_f32_e32 v8, v96, v112
	v_fmac_f32_e32 v9, v96, v116
	v_fmac_f32_e32 v16, v96, v120
	v_fmac_f32_e32 v17, v96, v124
	v_fmac_f32_e32 v24, v96, v128
	v_fmac_f32_e32 v25, v96, v132
	v_fmac_f32_e32 v32, v96, v136
	v_fmac_f32_e32 v33, v96, v140
	v_fmac_f32_e32 v67, v96, v144
	s_waitcnt vmcnt(14)
	v_fmac_f32_e32 v8, v97, v113
	v_fmac_f32_e32 v9, v97, v117
	v_fmac_f32_e32 v16, v97, v121
	v_fmac_f32_e32 v17, v97, v125
	v_fmac_f32_e32 v24, v97, v129
	v_fmac_f32_e32 v25, v97, v133
	v_fmac_f32_e32 v32, v97, v137
	v_fmac_f32_e32 v33, v97, v141
	v_fmac_f32_e32 v67, v97, v145
	s_waitcnt vmcnt(13)
	v_fmac_f32_e32 v8, v98, v114
	v_fmac_f32_e32 v9, v98, v118
	v_fmac_f32_e32 v16, v98, v122
	v_fmac_f32_e32 v17, v98, v126
	v_fmac_f32_e32 v24, v98, v130
	v_fmac_f32_e32 v25, v98, v134
	v_fmac_f32_e32 v32, v98, v138
	v_fmac_f32_e32 v33, v98, v142
	v_fmac_f32_e32 v67, v98, v146
	s_waitcnt vmcnt(12)
	v_fmac_f32_e32 v8, v99, v115
	v_fmac_f32_e32 v9, v99, v119
	v_fmac_f32_e32 v16, v99, v123
	v_fmac_f32_e32 v17, v99, v127
	v_fmac_f32_e32 v24, v99, v131
	v_fmac_f32_e32 v25, v99, v135
	v_fmac_f32_e32 v32, v99, v139
	v_fmac_f32_e32 v33, v99, v143
	v_fmac_f32_e32 v67, v99, v147
	ds_read_b128 v[112:115], v66 offset:16
	ds_read_b128 v[116:119], v66 offset:4112
	ds_read_b128 v[120:123], v66 offset:8208
	ds_read_b128 v[124:127], v66 offset:12304
	ds_read_b128 v[128:131], v66 offset:16400
	ds_read_b128 v[132:135], v66 offset:20496
	ds_read_b128 v[136:139], v66 offset:24592
	ds_read_b128 v[140:143], v66 offset:28688
	ds_read_b128 v[144:147], v66 offset:32784
	s_waitcnt lgkmcnt(0)
	s_waitcnt vmcnt(11)
	v_fmac_f32_e32 v8, v100, v112
	v_fmac_f32_e32 v9, v100, v116
	v_fmac_f32_e32 v16, v100, v120
	v_fmac_f32_e32 v17, v100, v124
	v_fmac_f32_e32 v24, v100, v128
	v_fmac_f32_e32 v25, v100, v132
	v_fmac_f32_e32 v32, v100, v136
	v_fmac_f32_e32 v33, v100, v140
	v_fmac_f32_e32 v67, v100, v144
	s_waitcnt vmcnt(10)
;   DI float* mod() const { return (float*)(ws + O_MOD); }
; DI void phase_init(const Ctx& c) {
;     ...
;       for (int k = kq * 128; k < kq * 128 + 128; ++k) {
;         const float wv = w[(size_t)k * 6144];
; #pragma unroll
;         for (int b = 0; b < 9; ++b) acc[b] += sc[b * 1024 + k] * wv;
;       }
; #pragma unroll
;       for (int b = 0; b < 9; ++b) red[(kq * 9 + b) * 64 + col] = acc[b];
;       __syncthreads();
;       for (int i = tid; i < 9 * 64; i += NTH) {
;         const int b = i >> 6, cc = i & 63;
;         float v = 0.f;
; #pragma unroll
;         for (int q = 0; q < 8; ++q) v += red[(q * 9 + b) * 64 + cc];
;         c.mod()[(size_t)(l * 9 + b) * 6144 + n0 + cc] = v + P.in[5][l * 6144 + n0 + cc];
	v_fmac_f32_e32 v8, v101, v113
	v_fmac_f32_e32 v9, v101, v117
	v_fmac_f32_e32 v16, v101, v121
	v_fmac_f32_e32 v17, v101, v125
	v_fmac_f32_e32 v24, v101, v129
	v_fmac_f32_e32 v25, v101, v133
	v_fmac_f32_e32 v32, v101, v137
	v_fmac_f32_e32 v33, v101, v141
	v_fmac_f32_e32 v67, v101, v145
	s_waitcnt vmcnt(9)
	v_fmac_f32_e32 v8, v102, v114
	v_fmac_f32_e32 v9, v102, v118
	v_fmac_f32_e32 v16, v102, v122
	v_fmac_f32_e32 v17, v102, v126
	v_fmac_f32_e32 v24, v102, v130
	v_fmac_f32_e32 v25, v102, v134
	v_fmac_f32_e32 v32, v102, v138
	v_fmac_f32_e32 v33, v102, v142
	v_fmac_f32_e32 v67, v102, v146
	s_waitcnt vmcnt(8)
	v_fmac_f32_e32 v8, v103, v115
	v_fmac_f32_e32 v9, v103, v119
	v_fmac_f32_e32 v16, v103, v123
	v_fmac_f32_e32 v17, v103, v127
	v_fmac_f32_e32 v24, v103, v131
	v_fmac_f32_e32 v25, v103, v135
	v_fmac_f32_e32 v32, v103, v139
	v_fmac_f32_e32 v33, v103, v143
	v_fmac_f32_e32 v67, v103, v147
	ds_read_b128 v[112:115], v66 offset:32
	ds_read_b128 v[116:119], v66 offset:4128
	ds_read_b128 v[120:123], v66 offset:8224
	ds_read_b128 v[124:127], v66 offset:12320
	ds_read_b128 v[128:131], v66 offset:16416
	ds_read_b128 v[132:135], v66 offset:20512
	ds_read_b128 v[136:139], v66 offset:24608
	ds_read_b128 v[140:143], v66 offset:28704
	ds_read_b128 v[144:147], v66 offset:32800
	s_waitcnt lgkmcnt(0)
	s_waitcnt vmcnt(7)
	v_fmac_f32_e32 v8, v104, v112
	v_fmac_f32_e32 v9, v104, v116
	v_fmac_f32_e32 v16, v104, v120
	v_fmac_f32_e32 v17, v104, v124
	v_fmac_f32_e32 v24, v104, v128
	v_fmac_f32_e32 v25, v104, v132
	v_fmac_f32_e32 v32, v104, v136
	v_fmac_f32_e32 v33, v104, v140
	v_fmac_f32_e32 v67, v104, v144
	s_waitcnt vmcnt(6)
	v_fmac_f32_e32 v8, v105, v113
	v_fmac_f32_e32 v9, v105, v117
	v_fmac_f32_e32 v16, v105, v121
	v_fmac_f32_e32 v17, v105, v125
	v_fmac_f32_e32 v24, v105, v129
	v_fmac_f32_e32 v25, v105, v133
	v_fmac_f32_e32 v32, v105, v137
	v_fmac_f32_e32 v33, v105, v141
	v_fmac_f32_e32 v67, v105, v145
	s_waitcnt vmcnt(5)
	v_fmac_f32_e32 v8, v106, v114
	v_fmac_f32_e32 v9, v106, v118
	v_fmac_f32_e32 v16, v106, v122
	v_fmac_f32_e32 v17, v106, v126
	v_fmac_f32_e32 v24, v106, v130
	v_fmac_f32_e32 v25, v106, v134
	v_fmac_f32_e32 v32, v106, v138
	v_fmac_f32_e32 v33, v106, v142
	v_fmac_f32_e32 v67, v106, v146
	s_waitcnt vmcnt(4)
	v_fmac_f32_e32 v8, v107, v115
	v_fmac_f32_e32 v9, v107, v119
	v_fmac_f32_e32 v16, v107, v123
	v_fmac_f32_e32 v17, v107, v127
	v_fmac_f32_e32 v24, v107, v131
	v_fmac_f32_e32 v25, v107, v135
	v_fmac_f32_e32 v32, v107, v139
	v_fmac_f32_e32 v33, v107, v143
	v_fmac_f32_e32 v67, v107, v147
	ds_read_b128 v[112:115], v66 offset:48
	ds_read_b128 v[116:119], v66 offset:4144
	ds_read_b128 v[120:123], v66 offset:8240
	ds_read_b128 v[124:127], v66 offset:12336
	ds_read_b128 v[128:131], v66 offset:16432
	ds_read_b128 v[132:135], v66 offset:20528
	ds_read_b128 v[136:139], v66 offset:24624
	ds_read_b128 v[140:143], v66 offset:28720
	ds_read_b128 v[144:147], v66 offset:32816
	s_waitcnt lgkmcnt(0)
	s_waitcnt vmcnt(3)
	v_fmac_f32_e32 v8, v108, v112
	v_fmac_f32_e32 v9, v108, v116
	v_fmac_f32_e32 v16, v108, v120
	v_fmac_f32_e32 v17, v108, v124
	v_fmac_f32_e32 v24, v108, v128
	v_fmac_f32_e32 v25, v108, v132
	v_fmac_f32_e32 v32, v108, v136
	v_fmac_f32_e32 v33, v108, v140
	v_fmac_f32_e32 v67, v108, v144
	s_waitcnt vmcnt(2)
	v_fmac_f32_e32 v8, v109, v113
	v_fmac_f32_e32 v9, v109, v117
	v_fmac_f32_e32 v16, v109, v121
	v_fmac_f32_e32 v17, v109, v125
	v_fmac_f32_e32 v24, v109, v129
	v_fmac_f32_e32 v25, v109, v133
	v_fmac_f32_e32 v32, v109, v137
	v_fmac_f32_e32 v33, v109, v141
	v_fmac_f32_e32 v67, v109, v145
	s_waitcnt vmcnt(1)
	v_fmac_f32_e32 v8, v110, v114
	v_fmac_f32_e32 v9, v110, v118
	v_fmac_f32_e32 v16, v110, v122
	v_fmac_f32_e32 v17, v110, v126
	v_fmac_f32_e32 v24, v110, v130
	v_fmac_f32_e32 v25, v110, v134
	v_fmac_f32_e32 v32, v110, v138
	v_fmac_f32_e32 v33, v110, v142
	v_fmac_f32_e32 v67, v110, v146
	s_waitcnt vmcnt(0)
	v_fmac_f32_e32 v8, v111, v115
	v_fmac_f32_e32 v9, v111, v119
	v_fmac_f32_e32 v16, v111, v123
	v_fmac_f32_e32 v17, v111, v127
	v_fmac_f32_e32 v24, v111, v131
	v_fmac_f32_e32 v25, v111, v135
	v_fmac_f32_e32 v32, v111, v139
	v_fmac_f32_e32 v33, v111, v143
	v_fmac_f32_e32 v67, v111, v147
	v_add_u32_e32 v66, 64, v66
	ds_write2st64_b32 v43, v8, v9 offset0:144 offset1:145
	ds_write2st64_b32 v43, v16, v17 offset0:146 offset1:147
	ds_write2st64_b32 v43, v24, v25 offset0:148 offset1:149
	ds_write2st64_b32 v43, v32, v33 offset0:150 offset1:151
	ds_write_b32 v43, v67 offset:38912
	s_waitcnt lgkmcnt(0)
	s_barrier
	s_and_saveexec_b64 s[16:17], s[8:9]
	s_cbranch_execz .LBB0_31
	s_mul_i32 s24, s23, 0x1800
	s_add_i32 s24, s24, s2
	v_or_b32_e32 v0, s24, v60
	v_readlane_b32 s52, v251, 14
	v_ashrrev_i32_e32 v1, 31, v0
	v_readlane_b32 s62, v251, 24
	v_readlane_b32 s63, v251, 25
	s_mul_i32 s23, s23, 9
	v_lshl_add_u64 v[2:3], s[2:3], 2, v[44:45]
	v_lshl_add_u64 v[0:1], v[0:1], 2, s[62:63]
	s_mov_b64 s[2:3], 0
	v_mov_b32_e32 v4, v36
	v_readlane_b32 s53, v251, 15
	v_readlane_b32 s54, v251, 16
	v_readlane_b32 s55, v251, 17
	v_readlane_b32 s56, v251, 18
	v_readlane_b32 s57, v251, 19
	v_readlane_b32 s58, v251, 20
	v_readlane_b32 s59, v251, 21
	v_readlane_b32 s60, v251, 22
	v_readlane_b32 s61, v251, 23
	v_readlane_b32 s64, v251, 26
	v_readlane_b32 s65, v251, 27
	v_readlane_b32 s66, v251, 28
	v_readlane_b32 s67, v251, 29
